# scan pass 1 triangular solve software-pipelined across columns (two accumulator sets; next column's independent products issued between the dependent fma and add)
# speedup vs baseline: 1.0069x; 1.0031x over previous
; #define LAS __attribute__((address_space(3)))
; __device__ __forceinline__ void scan_pass1(const ScanP& sp, int b, int h, int seg, LAS unsigned char* lds) {
;     ...
;                 for (int r = 0; r < 16; ++r) { const int c = crow(r, hh); NT[c * 32 + ln] = (c < ln) ? Z[r] : 0.f; }
;                 {
;                     const bool lowrow = ln < 16;
;                     u32x2 a_, b_;
;                     a_.x = lowrow ? 0u : pk2(-Z[0], -Z[1]); a_.y = lowrow ? 0u : pk2(-Z[2], -Z[3]);
;                     b_.x = lowrow ? 0u : pk2(-Z[4], -Z[5]); b_.y = lowrow ? 0u : pk2(-Z[6], -Z[7]);
;                     *(LAS u32x2*)(lds + O_N21 + (ln * 40 + 4 * hh) * 2) = a_;
;                     *(LAS u32x2*)(lds + O_N21 + (ln * 40 + 8 + 4 * hh) * 2) = b_;
;                 }
;                 asm volatile("s_waitcnt lgkmcnt(0)" ::: "memory");
;                 float Tr[16];
;                 const int tb = ln >> 4, tl = ln & 15;
;                 const LAS float* NTl = NT + tb * (16 * 32 + 16); asm volatile("" : "+v"(NTl));
;                 f32x4 nvc[4], nvn[4];
; #pragma unroll
;                 for (int m = 0; m < 4; ++m) { nvc[m] = (f32x4){0.f, 0.f, 0.f, 0.f}; nvn[m] = nvc[m]; }
; #pragma unroll
;                 for (int cc = 0; cc < 16; ++cc) {
;                     const int cl = 15 - cc;
;                     if (cl >= 1) {
; #pragma unroll
;                         for (int m = 0; m < 4; ++m) if (4 * m + 3 > cl - 1) nvn[m] = *(const LAS f32x4*)(NTl + (cl - 1) * 32 + 4 * m);
;                     }
;                     float s0 = (cl == tl) ? 1.f : 0.f, s1 = 0.f, s2 = 0.f, s3 = 0.f;
; #pragma unroll
;                     for (int m = 0; m < 4; ++m) {
;                         if (4 * m + 3 > cl) {
;                             if (4 * m + 0 > cl) s0 -= Tr[4 * m + 0] * nvc[m][0];
;                             if (4 * m + 1 > cl) s1 -= Tr[4 * m + 1] * nvc[m][1];
;                             if (4 * m + 2 > cl) s2 -= Tr[4 * m + 2] * nvc[m][2];
;                             if (4 * m + 3 > cl) s3 -= Tr[4 * m + 3] * nvc[m][3];
;                         }
;                     }
;                     Tr[cl] = (s0 + s1) + (s2 + s3);
;                     asm volatile("" : "+v"(Tr[cl]) :: "memory");
; #pragma unroll
;                     for (int m = 0; m < 4; ++m) nvc[m] = nvn[m];
;                 }
.LBB0_271:
	s_andn2_b64 vcc, exec, s[78:79]
	s_mov_b32 s78, 0x800000
	s_mov_b32 s79, 0x3f317217
	s_mov_b32 s37, 0x7f800000
	s_movk_i32 s38, 0x5ff
	s_mov_b32 s40, 0xbfb8aa3b
	s_cbranch_vccnz .LBB0_283
	s_setprio 2
	v_readlane_b32 s0, v254, 30
	v_cmp_lt_i32_e32 vcc, v2, v189
	s_movk_i32 s22, 0x840
	v_lshl_add_u32 v119, v189, 2, s0
	v_cndmask_b32_e32 v121, 0, v68, vcc
	v_lshl_add_u32 v123, v188, 9, v119
	ds_write_b32 v123, v121
	v_or_b32_e32 v121, 1, v2
	v_cmp_lt_i32_e32 vcc, v121, v189
	v_lshl_add_u32 v121, v121, 7, v119
	v_xor_b32_e32 v68, 0x80000000, v68
	v_cndmask_b32_e32 v123, 0, v69, vcc
	v_cmp_lt_i32_e32 vcc, v117, v189
	ds_write_b32 v121, v123
	v_lshl_add_u32 v117, v117, 7, v119
	v_cndmask_b32_e32 v121, 0, v70, vcc
	v_cmp_lt_i32_e32 vcc, v116, v189
	ds_write_b32 v117, v121
	v_lshl_add_u32 v116, v116, 7, v119
	v_cndmask_b32_e32 v117, 0, v71, vcc
	v_cmp_lt_i32_e32 vcc, v115, v189
	ds_write_b32 v116, v117
	v_lshl_add_u32 v115, v115, 7, v119
	v_cndmask_b32_e32 v116, 0, v72, vcc
	v_cmp_lt_i32_e32 vcc, v113, v189
	ds_write_b32 v115, v116
	v_lshl_add_u32 v113, v113, 7, v119
	v_cndmask_b32_e32 v115, 0, v73, vcc
	v_cmp_lt_i32_e32 vcc, v109, v189
	ds_write_b32 v113, v115
	v_lshl_add_u32 v109, v109, 7, v119
	v_cndmask_b32_e32 v113, 0, v74, vcc
	v_cmp_lt_i32_e32 vcc, v3, v189
	ds_write_b32 v109, v113
	v_lshl_add_u32 v3, v3, 7, v119
	v_cndmask_b32_e32 v109, 0, v75, vcc
	v_cmp_lt_i32_e32 vcc, v111, v189
	ds_write_b32 v3, v109
	v_mov_b32_e32 v118, s0
	v_cndmask_b32_e32 v3, 0, v76, vcc
	v_lshl_add_u32 v76, v111, 7, v119
	v_cmp_lt_i32_e32 vcc, v106, v189
	ds_write_b32 v76, v3
	v_lshl_add_u32 v76, v106, 7, v119
	v_cndmask_b32_e32 v3, 0, v77, vcc
	v_cmp_lt_i32_e32 vcc, v110, v189
	ds_write_b32 v76, v3
	v_lshl_add_u32 v76, v110, 7, v119
	v_cndmask_b32_e32 v3, 0, v78, vcc
	v_cmp_lt_i32_e32 vcc, v104, v189
	ds_write_b32 v76, v3
	v_lshl_add_u32 v76, v104, 7, v119
	v_cndmask_b32_e32 v3, 0, v79, vcc
	v_cmp_lt_i32_e32 vcc, v114, v189
	ds_write_b32 v76, v3
	v_lshl_add_u32 v76, v114, 7, v119
	v_cndmask_b32_e32 v3, 0, v80, vcc
	v_cmp_lt_i32_e32 vcc, v112, v189
	ds_write_b32 v76, v3
	v_lshl_add_u32 v76, v112, 7, v119
	v_cndmask_b32_e32 v3, 0, v81, vcc
	v_cmp_lt_i32_e32 vcc, v107, v189
	ds_write_b32 v76, v3
	v_lshl_add_u32 v76, v107, 7, v119
	v_cndmask_b32_e32 v3, 0, v82, vcc
	v_cmp_lt_i32_e32 vcc, v105, v189
	ds_write_b32 v76, v3
	v_lshl_add_u32 v76, v105, 7, v119
	v_cndmask_b32_e32 v3, 0, v83, vcc
	ds_write_b32 v76, v3
	v_xor_b32_e32 v3, 0x80000000, v69
	v_cvt_pk_bf16_f32 v3, v68, v3
	v_cmp_gt_u32_e64 s[0:1], 16, v189
	v_xor_b32_e32 v69, 0x80000000, v71
	v_xor_b32_e32 v71, 0x80000000, v75
	v_cndmask_b32_e64 v68, v3, 0, s[0:1]
	v_xor_b32_e32 v3, 0x80000000, v70
	v_cvt_pk_bf16_f32 v3, v3, v69
	v_cndmask_b32_e64 v69, v3, 0, s[0:1]
	v_xor_b32_e32 v3, 0x80000000, v72
	v_xor_b32_e32 v70, 0x80000000, v73
	v_cvt_pk_bf16_f32 v3, v3, v70
	v_cndmask_b32_e64 v70, v3, 0, s[0:1]
	v_xor_b32_e32 v3, 0x80000000, v74
	v_mad_u32_u24 v2, v189, 40, v2
	v_cvt_pk_bf16_f32 v3, v3, v71
	v_lshl_add_u32 v2, v2, 1, 0
	v_cndmask_b32_e64 v71, v3, 0, s[0:1]
	v_add_u32_e32 v2, 0x1aa00, v2
	ds_write2_b64 v2, v[68:69], v[70:71] offset1:2
	v_lshrrev_b32_e32 v2, 4, v189
	v_mad_u32_u24 v109, v2, s22, v118
	v_and_b32_e32 v118, 15, v108
	s_waitcnt lgkmcnt(0)
	ds_read_b128 v[104:107], v109 offset:1840
	ds_read_b128 v[110:113], v109 offset:1712
	ds_read_b128 v[114:117], v109 offset:1584
	ds_read_b128 v[150:153], v109 offset:1456
	v_cmp_eq_u32_e64 s[100:101], 15, v118
	s_nop 1
	v_cndmask_b32_e64 v250, 0, 1.0, s[100:101]
	v_mov_b32_e32 v2, v250
	ds_read_b128 v[154:157], v109 offset:1312
	ds_read_b128 v[206:209], v109 offset:1328
	v_cmp_eq_u32_e64 s[22:23], 14, v118
	s_nop 1
	v_cndmask_b32_e64 v119, 0, 1.0, s[22:23]
	s_waitcnt lgkmcnt(5)
	v_fma_f32 v123, -v2, v107, 0
	ds_read_b128 v[222:225], v109 offset:1184
	ds_read_b128 v[226:229], v109 offset:1200
	v_cmp_eq_u32_e64 s[100:101], 13, v118
	s_waitcnt lgkmcnt(6)
	v_fma_f32 v221, -v2, v113, 0
	v_add_f32_e32 v3, v123, v119
	v_cndmask_b32_e64 v250, 0, 1.0, s[100:101]
	v_add_f32_e32 v250, v221, v250
	v_fma_f32 v193, -v3, v112, 0
	ds_read_b128 v[230:233], v109 offset:1056
	ds_read_b128 v[234:237], v109 offset:1072
	v_cmp_eq_u32_e64 s[22:23], 12, v118
	s_waitcnt lgkmcnt(7)
	v_fma_f32 v121, -v3, v116, 0
	v_fma_f32 v123, -v2, v117, 0
	v_add_f32_e32 v71, v193, v250
	v_cndmask_b32_e64 v119, 0, 1.0, s[22:23]
	v_add_f32_e32 v119, v121, v119
	v_add_f32_e32 v119, v123, v119
	v_fma_f32 v80, -v71, v115, 0
	ds_read_b128 v[238:241], v109 offset:928
	ds_read_b128 v[242:245], v109 offset:944
	v_cmp_eq_u32_e64 s[100:101], 11, v118
	s_waitcnt lgkmcnt(8)
	v_fma_f32 v192, -v71, v151, 0
	v_fma_f32 v193, -v3, v152, 0
	v_fma_f32 v221, -v2, v153, 0
	v_add_f32_e32 v78, v80, v119
	v_cndmask_b32_e64 v250, 0, 1.0, s[100:101]
	v_add_f32_e32 v250, v192, v250
	v_add_f32_e32 v250, v193, v250
	v_add_f32_e32 v250, v221, v250
	v_fma_f32 v191, -v78, v150, 0
	ds_read_b128 v[246:249], v109 offset:784
	ds_read_b128 v[104:107], v109 offset:800
	ds_read_b128 v[110:113], v109 offset:816
	v_cmp_eq_u32_e64 s[22:23], 10, v118
	s_waitcnt lgkmcnt(9)
	v_fma_f32 v75, -v78, v206, 0
	v_fma_f32 v80, -v71, v207, 0
	v_fma_f32 v121, -v3, v208, 0
	v_fma_f32 v123, -v2, v209, 0
	v_add_f32_e32 v77, v191, v250
	v_cndmask_b32_e64 v119, 0, 1.0, s[22:23]
	v_add_f32_e32 v119, v75, v119
	v_add_f32_e32 v119, v80, v119
	v_add_f32_e32 v119, v121, v119
	v_fma_f32 v123, -v77, v157, v123
	v_cmp_eq_u32_e64 s[100:101], 9, v118
	s_waitcnt lgkmcnt(7)
; #define LAS __attribute__((address_space(3)))
; __device__ __forceinline__ void scan_pass1(const ScanP& sp, int b, int h, int seg, LAS unsigned char* lds) {
;     ...
;                 for (int cc = 0; cc < 16; ++cc) {
;                     const int cl = 15 - cc;
;                     if (cl >= 1) {
; #pragma unroll
;                         for (int m = 0; m < 4; ++m) if (4 * m + 3 > cl - 1) nvn[m] = *(const LAS f32x4*)(NTl + (cl - 1) * 32 + 4 * m);
;                     }
;                     float s0 = (cl == tl) ? 1.f : 0.f, s1 = 0.f, s2 = 0.f, s3 = 0.f;
; #pragma unroll
;                     for (int m = 0; m < 4; ++m) {
;                         if (4 * m + 3 > cl) {
;                             if (4 * m + 0 > cl) s0 -= Tr[4 * m + 0] * nvc[m][0];
;                             if (4 * m + 1 > cl) s1 -= Tr[4 * m + 1] * nvc[m][1];
;                             if (4 * m + 2 > cl) s2 -= Tr[4 * m + 2] * nvc[m][2];
;                             if (4 * m + 3 > cl) s3 -= Tr[4 * m + 3] * nvc[m][3];
;                         }
;                     }
;                     Tr[cl] = (s0 + s1) + (s2 + s3);
;                     asm volatile("" : "+v"(Tr[cl]) :: "memory");
; #pragma unroll
;                     for (int m = 0; m < 4; ++m) nvc[m] = nvn[m];
;                 }
;                 if (hh == 0) {
	v_fma_f32 v191, -v78, v226, 0
	v_fma_f32 v192, -v71, v227, 0
	v_fma_f32 v193, -v3, v228, 0
	v_fma_f32 v221, -v2, v229, 0
	v_add_f32_e32 v79, v123, v119
	v_fma_f32 v221, -v77, v225, v221
	v_cndmask_b32_e64 v250, 0, 1.0, s[100:101]
	v_add_f32_e32 v250, v191, v250
	v_add_f32_e32 v250, v192, v250
	v_add_f32_e32 v250, v221, v250
	v_fma_f32 v193, -v79, v224, v193
	ds_read_b128 v[114:117], v109 offset:656
	ds_read_b128 v[150:153], v109 offset:672
	ds_read_b128 v[154:157], v109 offset:688
	v_cmp_eq_u32_e64 s[22:23], 8, v118
	s_waitcnt lgkmcnt(8)
	v_fma_f32 v75, -v78, v234, 0
	v_fma_f32 v80, -v71, v235, 0
	v_fma_f32 v121, -v3, v236, 0
	v_fma_f32 v123, -v2, v237, 0
	v_fma_f32 v121, -v79, v232, v121
	v_add_f32_e32 v81, v193, v250
	v_fma_f32 v123, -v77, v233, v123
	v_cndmask_b32_e64 v119, 0, 1.0, s[22:23]
	v_add_f32_e32 v119, v75, v119
	v_add_f32_e32 v119, v121, v119
	v_add_f32_e32 v119, v123, v119
	v_fma_f32 v80, -v81, v231, v80
	ds_read_b128 v[206:209], v109 offset:528
	ds_read_b128 v[222:225], v109 offset:544
	ds_read_b128 v[226:229], v109 offset:560
	v_cmp_eq_u32_e64 s[100:101], 7, v118
	s_waitcnt lgkmcnt(9)
	v_fma_f32 v191, -v78, v242, 0
	v_fma_f32 v192, -v71, v243, 0
	v_fma_f32 v193, -v3, v244, 0
	v_fma_f32 v221, -v2, v245, 0
	v_fma_f32 v192, -v81, v239, v192
	v_add_f32_e32 v82, v80, v119
	v_fma_f32 v193, -v79, v240, v193
	v_fma_f32 v221, -v77, v241, v221
	v_cndmask_b32_e64 v250, 0, 1.0, s[100:101]
	v_add_f32_e32 v250, v192, v250
	v_add_f32_e32 v250, v193, v250
	v_add_f32_e32 v250, v221, v250
	v_fma_f32 v191, -v82, v238, v191
	v_cmp_eq_u32_e64 s[22:23], 6, v118
	s_waitcnt lgkmcnt(6)
	v_fma_f32 v75, -v78, v110, 0
	v_fma_f32 v80, -v71, v111, 0
	v_fma_f32 v121, -v3, v112, 0
	v_fma_f32 v123, -v2, v113, 0
	v_fma_f32 v75, -v82, v104, v75
	v_fma_f32 v80, -v81, v105, v80
	v_add_f32_e32 v76, v191, v250
	v_fma_f32 v121, -v79, v106, v121
	v_fma_f32 v123, -v77, v107, v123
	v_cndmask_b32_e64 v119, 0, 1.0, s[22:23]
	v_add_f32_e32 v119, v75, v119
	v_add_f32_e32 v119, v80, v119
	v_add_f32_e32 v119, v121, v119
	v_fma_f32 v123, -v76, v249, v123
	ds_read_b128 v[230:233], v109 offset:400
	ds_read_b128 v[234:237], v109 offset:416
	ds_read_b128 v[238:241], v109 offset:432
	v_cmp_eq_u32_e64 s[100:101], 5, v118
	s_waitcnt lgkmcnt(6)
	v_fma_f32 v191, -v78, v154, 0
	v_fma_f32 v192, -v71, v155, 0
	v_fma_f32 v193, -v3, v156, 0
	v_fma_f32 v221, -v2, v157, 0
	v_fma_f32 v191, -v82, v150, v191
	v_fma_f32 v192, -v81, v151, v192
	v_add_f32_e32 v83, v123, v119
	v_fma_f32 v193, -v79, v152, v193
	v_fma_f32 v221, -v77, v153, v221
	v_fma_f32 v221, -v76, v117, v221
	v_cndmask_b32_e64 v250, 0, 1.0, s[100:101]
	v_add_f32_e32 v250, v191, v250
	v_add_f32_e32 v250, v192, v250
	v_add_f32_e32 v250, v221, v250
	v_fma_f32 v193, -v83, v116, v193
	ds_read_b128 v[242:245], v109 offset:256
	ds_read_b128 v[246:249], v109 offset:272
	ds_read_b128 v[104:107], v109 offset:288
	ds_read_b128 v[110:113], v109 offset:304
	v_cmp_eq_u32_e64 s[22:23], 4, v118
	s_waitcnt lgkmcnt(7)
	v_fma_f32 v75, -v78, v226, 0
	v_fma_f32 v80, -v71, v227, 0
	v_fma_f32 v121, -v3, v228, 0
	v_fma_f32 v123, -v2, v229, 0
	v_fma_f32 v75, -v82, v222, v75
	v_fma_f32 v80, -v81, v223, v80
	v_fma_f32 v121, -v79, v224, v121
	v_add_f32_e32 v70, v193, v250
	v_fma_f32 v123, -v77, v225, v123
	v_fma_f32 v121, -v83, v208, v121
	v_fma_f32 v123, -v76, v209, v123
	v_cndmask_b32_e64 v119, 0, 1.0, s[22:23]
	v_add_f32_e32 v119, v75, v119
	v_add_f32_e32 v119, v121, v119
	v_add_f32_e32 v119, v123, v119
	v_fma_f32 v80, -v70, v207, v80
	v_cmp_eq_u32_e64 s[100:101], 3, v118
	s_waitcnt lgkmcnt(4)
	v_fma_f32 v191, -v78, v238, 0
	v_fma_f32 v192, -v71, v239, 0
	v_fma_f32 v193, -v3, v240, 0
	v_fma_f32 v221, -v2, v241, 0
	v_fma_f32 v191, -v82, v234, v191
	v_fma_f32 v192, -v81, v235, v192
	v_fma_f32 v193, -v79, v236, v193
	v_add_f32_e32 v74, v80, v119
	v_fma_f32 v221, -v77, v237, v221
	v_fma_f32 v192, -v70, v231, v192
	v_fma_f32 v193, -v83, v232, v193
	v_fma_f32 v221, -v76, v233, v221
	v_cndmask_b32_e64 v250, 0, 1.0, s[100:101]
	v_add_f32_e32 v250, v192, v250
	v_add_f32_e32 v250, v193, v250
	v_add_f32_e32 v250, v221, v250
	v_fma_f32 v191, -v74, v230, v191
	ds_read_b128 v[114:117], v109 offset:128
	ds_read_b128 v[150:153], v109 offset:144
	ds_read_b128 v[154:157], v109 offset:160
	ds_read_b128 v[206:209], v109 offset:176
	v_cmp_eq_u32_e64 s[22:23], 2, v118
	s_waitcnt lgkmcnt(4)
	v_fma_f32 v75, -v78, v110, 0
	v_fma_f32 v80, -v71, v111, 0
	v_fma_f32 v121, -v3, v112, 0
	v_fma_f32 v123, -v2, v113, 0
	v_fma_f32 v75, -v82, v104, v75
	v_fma_f32 v80, -v81, v105, v80
	v_fma_f32 v121, -v79, v106, v121
	v_fma_f32 v123, -v77, v107, v123
	v_add_f32_e32 v69, v191, v250
	v_fma_f32 v75, -v74, v246, v75
	v_fma_f32 v80, -v70, v247, v80
	v_fma_f32 v121, -v83, v248, v121
	v_fma_f32 v123, -v76, v249, v123
	v_cndmask_b32_e64 v119, 0, 1.0, s[22:23]
	v_add_f32_e32 v119, v75, v119
	v_add_f32_e32 v119, v80, v119
	v_add_f32_e32 v119, v121, v119
	v_fma_f32 v123, -v69, v245, v123
	ds_read_b128 v[222:225], v109 offset:0
	ds_read_b128 v[226:229], v109 offset:16
	ds_read_b128 v[230:233], v109 offset:32
	ds_read_b128 v[234:237], v109 offset:48
	v_cmp_eq_u32_e64 s[100:101], 1, v118
	s_waitcnt lgkmcnt(4)
	v_fma_f32 v191, -v78, v206, 0
	v_fma_f32 v192, -v71, v207, 0
	v_fma_f32 v193, -v3, v208, 0
	v_fma_f32 v221, -v2, v209, 0
	v_fma_f32 v191, -v82, v154, v191
	v_fma_f32 v192, -v81, v155, v192
	v_fma_f32 v193, -v79, v156, v193
	v_fma_f32 v221, -v77, v157, v221
	v_add_f32_e32 v73, v123, v119
	v_fma_f32 v191, -v74, v150, v191
	v_fma_f32 v192, -v70, v151, v192
	v_fma_f32 v193, -v83, v152, v193
	v_fma_f32 v221, -v76, v153, v221
	v_fma_f32 v221, -v69, v117, v221
	v_cndmask_b32_e64 v250, 0, 1.0, s[100:101]
	v_add_f32_e32 v250, v191, v250
	v_add_f32_e32 v250, v192, v250
	v_add_f32_e32 v250, v221, v250
	v_fma_f32 v193, -v73, v116, v193
	v_cmp_eq_u32_e64 s[22:23], 0, v118
	s_waitcnt lgkmcnt(0)
	v_fma_f32 v75, -v78, v234, 0
	v_fma_f32 v80, -v71, v235, 0
	v_fma_f32 v121, -v3, v236, 0
	v_fma_f32 v123, -v2, v237, 0
	v_fma_f32 v75, -v82, v230, v75
	v_fma_f32 v80, -v81, v231, v80
	v_fma_f32 v121, -v79, v232, v121
	v_fma_f32 v123, -v77, v233, v123
	v_fma_f32 v75, -v74, v226, v75
	v_add_f32_e32 v68, v193, v250
	v_fma_f32 v80, -v70, v227, v80
	v_fma_f32 v121, -v83, v228, v121
	v_fma_f32 v123, -v76, v229, v123
	v_fma_f32 v121, -v73, v224, v121
	v_fma_f32 v123, -v69, v225, v123
	v_cndmask_b32_e64 v119, 0, 1.0, s[22:23]
	v_add_f32_e32 v119, v75, v119
	v_add_f32_e32 v119, v121, v119
	v_add_f32_e32 v119, v123, v119
	v_fma_f32 v80, -v68, v223, v80
	v_add_f32_e32 v72, v80, v119
	v_cmp_lt_u32_e32 vcc, 15, v189
	v_cmp_gt_u32_e64 s[22:23], 32, v108
	s_and_saveexec_b64 s[24:25], s[22:23]
	s_cbranch_execz .LBB0_282
; #define LAS __attribute__((address_space(3)))
; __device__ __forceinline__ unsigned pk2(float lo, float hi) { f32x2 v = {lo, hi}; bf16x2_t b = __builtin_convertvector(v, bf16x2_t); return __builtin_bit_cast(unsigned, b); }
; __device__ __forceinline__ void scan_pass1(const ScanP& sp, int b, int h, int seg, LAS unsigned char* lds) {
;     ...
;                 if (hh == 0) {
; #pragma unroll
;                     for (int q = 0; q < 4; ++q) {
;                         const bool mine = (q >> 1) == tb; const int o8 = 8 * (q & 1);
;                         u32x4 o; o.x = mine ? pk2(Tr[o8], Tr[o8 + 1]) : 0u; o.y = mine ? pk2(Tr[o8 + 2], Tr[o8 + 3]) : 0u; o.z = mine ? pk2(Tr[o8 + 4], Tr[o8 + 5]) : 0u; o.w = mine ? pk2(Tr[o8 + 6], Tr[o8 + 7]) : 0u;
;                         *(LAS u32x4*)(lds + O_TM + ln * 80 + 16 * q) = o;
;                     }
	v_cvt_pk_bf16_f32 v68, v72, v68
	v_cvt_pk_bf16_f32 v69, v73, v69
	v_cvt_pk_bf16_f32 v70, v74, v70
	v_cndmask_b32_e64 v72, 0, v68, s[0:1]
	v_cndmask_b32_e64 v73, 0, v69, s[0:1]
	v_cndmask_b32_e64 v74, 0, v70, s[0:1]
	s_and_saveexec_b64 s[22:23], vcc
	s_xor_b64 s[22:23], exec, s[22:23]
	v_mov_b32_e32 v75, s93
	v_mov_b64_e32 v[106:107], v[74:75]
	v_mov_b64_e32 v[104:105], v[72:73]
	s_or_saveexec_b64 s[22:23], s[22:23]
	v_mov_b32_e32 v80, 0
	v_cvt_pk_bf16_f32 v75, v83, v76
	v_cvt_pk_bf16_f32 v76, v82, v81
	s_xor_b64 exec, exec, s[22:23]
	v_mov_b32_e32 v70, 0
	v_mov_b64_e32 v[106:107], v[74:75]
	v_cvt_pk_bf16_f32 v80, v82, v81
	v_mov_b32_e32 v69, v70
	v_mov_b32_e32 v68, v70
	v_mov_b64_e32 v[104:105], v[72:73]
	s_or_b64 exec, exec, s[22:23]
	s_movk_i32 s22, 0x50
	v_mad_u32_u24 v72, v189, s22, 0
	v_cvt_pk_bf16_f32 v77, v79, v77
	v_cvt_pk_bf16_f32 v78, v78, v71
	v_cvt_pk_bf16_f32 v79, v3, v2
	v_add_u32_e32 v72, 0x11800, v72
	v_cndmask_b32_e64 v81, 0, v77, s[0:1]
	v_cndmask_b32_e64 v82, 0, v78, s[0:1]
	v_cndmask_b32_e64 v83, 0, v79, s[0:1]
	v_mov_b32_e32 v71, s93
	ds_write_b128 v72, v[104:107]
	ds_write_b128 v72, v[80:83] offset:16
	s_and_saveexec_b64 s[0:1], vcc
	s_xor_b64 s[0:1], exec, s[0:1]
	v_mov_b32_e32 v71, v75
	s_andn2_saveexec_b64 s[0:1], s[0:1]
	v_mov_b32_e32 v79, 0
	v_mov_b32_e32 v78, v79
	v_mov_b32_e32 v77, v79
	v_mov_b32_e32 v76, v79
	s_or_b64 exec, exec, s[0:1]
	v_mul_u32_u24_e32 v2, 0x50, v189
	s_add_i32 s0, 0, 0x11800
	v_add_u32_e32 v2, s0, v2
	ds_write_b128 v2, v[68:71] offset:32
	ds_write_b128 v2, v[76:79] offset:48
